# retention unit prologue de-serialised: first K and V tile staged by one batch of 8 LDS-DMA loads instead of two load-wait-ds_write ladders
# speedup vs baseline: 1.0110x; 1.0110x over previous
.LBB0_862:
	s_xor_b64 s[46:47], s[4:5], -1
	s_and_b64 s[4:5], s[4:5], exec
	v_mov_b32_e32 v20, v170
	s_cselect_b32 s9, s7, s8
	v_readfirstlane_b32 s4, v20
	s_ashr_i32 s4, s4, 2
	s_and_b32 s4, s4, -16
	v_and_b32_e32 v21, 15, v20
	s_add_i32 s4, s4, s9
	v_or_b32_e32 v172, s4, v21
	v_ashrrev_i32_e32 v173, 31, v172
	v_bfe_u32 v22, v20, 4, 2
	s_waitcnt lgkmcnt(0)
	v_lshlrev_b64 v[0:1], 14, v[172:173]
	v_lshl_add_u64 v[0:1], s[22:23], 0, v[0:1]
	v_lshlrev_b32_e32 v8, 4, v22
	v_lshl_add_u64 v[0:1], v[0:1], 0, v[8:9]
	v_mov_b32_e32 v16, v170
	global_load_dwordx4 v[102:105], v[0:1], off
	global_load_dwordx4 v[98:101], v[0:1], off offset:64
	global_load_dwordx4 v[94:97], v[0:1], off offset:128
	global_load_dwordx4 v[90:93], v[0:1], off offset:192
	global_load_dwordx4 v[86:89], v[0:1], off offset:256
	global_load_dwordx4 v[82:85], v[0:1], off offset:320
	global_load_dwordx4 v[78:81], v[0:1], off offset:384
	global_load_dwordx4 v[74:77], v[0:1], off offset:448
	v_lshrrev_b32_e32 v106, 5, v170
	v_and_b32_e32 v107, 31, v170
	v_and_b32_e32 v108, 15, v106
	v_xor_b32_e32 v108, v107, v108
	v_and_b32_e32 v109, 7, v106
	v_lshlrev_b32_e32 v109, 1, v109
	v_xor_b32_e32 v107, v107, v109
	v_lshlrev_b32_e32 v109, 14, v106
	v_lshl_or_b32 v106, v108, 4, v109
	v_lshl_or_b32 v107, v107, 4, v109
	v_readlane_b32 s16, v254, 60
	s_lshl_b32 s16, s16, 10
	s_mov_b32 m0, s16
	v_add_u32_e32 v108, 0x40000, v106
	global_load_lds_dwordx4 v106, s[24:25]
	s_add_i32 m0, m0, 0x2000
	v_add_u32_e32 v109, 0x80000, v106
	global_load_lds_dwordx4 v108, s[24:25]
	s_add_i32 m0, m0, 0x2000
	v_add_u32_e32 v110, 0xc0000, v106
	global_load_lds_dwordx4 v109, s[24:25]
	s_add_i32 m0, m0, 0x2000
	v_add_u32_e32 v111, 0x40000, v107
	global_load_lds_dwordx4 v110, s[24:25]
	s_add_i32 m0, s16, 0x10800
	v_add_u32_e32 v112, 0x80000, v107
	global_load_lds_dwordx4 v107, s[26:27]
	s_add_i32 m0, m0, 0x2000
	v_add_u32_e32 v113, 0xc0000, v107
	global_load_lds_dwordx4 v111, s[26:27]
	s_add_i32 m0, m0, 0x2000
	s_nop 0
	global_load_lds_dwordx4 v112, s[26:27]
	s_add_i32 m0, m0, 0x2000
	s_nop 0
	global_load_lds_dwordx4 v113, s[26:27]
	v_lshlrev_b32_e32 v194, 2, v22
	s_add_i32 s5, s9, 0x80
	v_readfirstlane_b32 s40, v179
	v_readfirstlane_b32 s44, v180
	v_readfirstlane_b32 s41, v181
	v_readfirstlane_b32 s37, v190
	v_readfirstlane_b32 s42, v191
	v_readfirstlane_b32 s36, v192
	v_readfirstlane_b32 s43, v193
	v_mov_b32_e32 v171, v172
	s_mov_b32 s45, 0
	s_mov_b32 s48, 0
	v_lshlrev_b32_e32 v0, 9, v21
	v_and_b32_e32 v1, 48, v20
	v_lshlrev_b32_e32 v246, 4, v21
	v_xor_b32_e32 v1, v1, v246
	v_add3_u32 v195, 0, v0, v1
	v_bfe_u32 v0, v20, 2, 2
	v_or_b32_e32 v0, v194, v0
	v_lshlrev_b32_e32 v1, 3, v20
	v_and_b32_e32 v246, 7, v0
	v_lshlrev_b32_e32 v246, 5, v246
	v_lshl_or_b32 v0, v0, 9, v246
	v_and_b32_e32 v1, 24, v1
	v_mov_b32_e32 v10, v9
	v_mov_b32_e32 v11, v9
	v_add3_u32 v173, s97, v0, v1
	v_add_u32_e32 v0, s4, v21
	v_mov_b32_e32 v8, v9
	v_mov_b64_e32 v[44:45], v[10:11]
	v_mov_b64_e32 v[48:49], v[10:11]
	v_mov_b64_e32 v[52:53], v[10:11]
	v_mov_b64_e32 v[56:57], v[10:11]
	v_mov_b64_e32 v[60:61], v[10:11]
	v_mov_b64_e32 v[64:65], v[10:11]
	v_mov_b64_e32 v[68:69], v[10:11]
	v_mov_b64_e32 v[72:73], v[10:11]
	v_mov_b64_e32 v[40:41], v[10:11]
	v_mov_b64_e32 v[36:37], v[10:11]
	v_mov_b64_e32 v[32:33], v[10:11]
	v_mov_b64_e32 v[28:29], v[10:11]
	v_mov_b64_e32 v[24:25], v[10:11]
	v_mov_b64_e32 v[20:21], v[10:11]
	v_mov_b64_e32 v[16:17], v[10:11]
	s_lshr_b32 s17, s5, 6
	v_mov_b64_e32 v[42:43], v[8:9]
	v_mov_b64_e32 v[46:47], v[8:9]
	v_mov_b64_e32 v[50:51], v[8:9]
	v_mov_b64_e32 v[54:55], v[8:9]
	v_mov_b64_e32 v[58:59], v[8:9]
	v_mov_b64_e32 v[62:63], v[8:9]
	v_mov_b64_e32 v[66:67], v[8:9]
	v_mov_b64_e32 v[70:71], v[8:9]
	v_mov_b64_e32 v[38:39], v[8:9]
	v_mov_b64_e32 v[34:35], v[8:9]
	v_mov_b64_e32 v[30:31], v[8:9]
	v_mov_b64_e32 v[26:27], v[8:9]
	v_mov_b64_e32 v[22:23], v[8:9]
	v_mov_b64_e32 v[18:19], v[8:9]
	v_mov_b64_e32 v[14:15], v[8:9]
	v_mov_b64_e32 v[12:13], v[10:11]
	s_or_b32 s16, s4, 15
	s_add_i32 s17, s17, -1
	v_sub_u32_e32 v196, v0, v194
	v_mov_b64_e32 v[10:11], v[8:9]
	v_lshrrev_b32_e32 v106, 5, v170
	v_and_b32_e32 v107, 31, v170
	v_and_b32_e32 v108, 15, v106
	v_xor_b32_e32 v108, v107, v108
	v_and_b32_e32 v109, 7, v106
	v_lshlrev_b32_e32 v109, 1, v109
	v_xor_b32_e32 v107, v107, v109
	v_lshlrev_b32_e32 v109, 14, v106
	v_lshl_or_b32 v106, v108, 4, v109
	v_lshl_or_b32 v107, v107, 4, v109
	s_waitcnt vmcnt(0) lgkmcnt(0)
	s_barrier
	s_branch .LBB0_865
